# ret_u second-round half-units moved to workgroups 128..255 (balance against ret_scan); ret_scan processes two 16-step batches per trip (32 loads in flight)
# speedup vs baseline: 1.0108x; 1.0034x over previous
.Lru_nopf:
	s_mov_b32 s10, 0x15ed8000
	s_mov_b32 s10, 0x16158000
	s_nop 0
	s_mov_b32 s10, 0x163d8000
	s_nop 0
	s_mov_b32 s10, 0x16658000
	s_nop 0
	v_lshl_add_u64 v[120:121], v[102:103], 0, s[8:9]
	s_nop 0
	s_mov_b32 s10, 0x136d8000
	v_add_u32_e32 v85, 7, v146
	s_nop 0
	v_cvt_f32_u32_e32 v85, v85
	v_add_u32_e32 v84, -7, v147
	v_cvt_f32_u32_e32 v84, v84
	v_mul_f32_e32 v86, v144, v85
	v_cmp_gt_f32_e32 vcc, s96, v86
	s_mov_b32 s10, 0x13958000
	v_cndmask_b32_e32 v86, 0, v225, vcc
	v_fmac_f32_e32 v86, v144, v85
	v_exp_f32_e32 v85, v86
	v_cndmask_b32_e32 v86, 0, v226, vcc
	s_add_u32 s8, s8, 64
	v_ldexp_f32 v104, v85, v86
	v_add_u32_e32 v85, 6, v146
	v_cvt_f32_u32_e32 v85, v85
	s_addc_u32 s9, s9, 0
	s_cmpk_eq_i32 s8, 0x100
	v_mul_f32_e32 v86, v144, v85
	v_cmp_gt_f32_e32 vcc, s96, v86
	s_nop 0
	v_and_b32_e32 v149, 0xffff0000, v83
	v_cndmask_b32_e32 v86, 0, v225, vcc
	v_fmac_f32_e32 v86, v144, v85
	v_exp_f32_e32 v85, v86
	v_cndmask_b32_e32 v86, 0, v226, vcc
	v_ldexp_f32 v105, v85, v86
	v_mul_f32_e32 v85, v145, v84
	v_cmp_gt_f32_e32 vcc, s96, v85
	s_nop 1
	v_cndmask_b32_e32 v85, 0, v225, vcc
	v_fmac_f32_e32 v85, v145, v84
	v_exp_f32_e32 v84, v85
	v_cndmask_b32_e32 v85, 0, v226, vcc
	v_ldexp_f32 v106, v84, v85
	v_add_u32_e32 v84, -6, v147
	v_cvt_f32_u32_e32 v84, v84
	v_mul_f32_e32 v85, v145, v84
	v_cmp_gt_f32_e32 vcc, s96, v85
	s_nop 1
	v_cndmask_b32_e32 v85, 0, v225, vcc
	v_fmac_f32_e32 v85, v145, v84
	v_exp_f32_e32 v84, v85
	v_cndmask_b32_e32 v85, 0, v226, vcc
	v_ldexp_f32 v107, v84, v85
	v_lshlrev_b32_e32 v84, 16, v80
	v_and_b32_e32 v85, 0xffff0000, v80
	v_pk_mul_f32 v[86:87], v[104:105], v[84:85]
	v_pk_mul_f32 v[84:85], v[106:107], v[84:85]
	v_cvt_pk_bf16_f32 v80, v86, v87
	v_add_u32_e32 v86, 5, v146
	v_cvt_f32_u32_e32 v86, v86
	v_cvt_pk_bf16_f32 v84, v84, v85
	v_add_u32_e32 v85, -5, v147
	v_cvt_f32_u32_e32 v85, v85
	v_mul_f32_e32 v87, v144, v86
	v_cmp_gt_f32_e32 vcc, s96, v87
	s_nop 1
	v_cndmask_b32_e32 v87, 0, v225, vcc
	v_fmac_f32_e32 v87, v144, v86
	v_exp_f32_e32 v86, v87
	v_cndmask_b32_e32 v87, 0, v226, vcc
	v_ldexp_f32 v108, v86, v87
	v_add_u32_e32 v86, 4, v146
	v_cvt_f32_u32_e32 v86, v86
	v_mul_f32_e32 v87, v144, v86
	v_cmp_gt_f32_e32 vcc, s96, v87
	s_nop 1
	v_cndmask_b32_e32 v87, 0, v225, vcc
	v_fmac_f32_e32 v87, v144, v86
	v_exp_f32_e32 v86, v87
	v_cndmask_b32_e32 v87, 0, v226, vcc
	v_ldexp_f32 v109, v86, v87
	v_mul_f32_e32 v86, v145, v85
	v_cmp_gt_f32_e32 vcc, s96, v86
	v_and_b32_e32 v87, 0xffff0000, v81
	s_nop 0
	v_cndmask_b32_e32 v86, 0, v225, vcc
	v_fmac_f32_e32 v86, v145, v85
	v_exp_f32_e32 v85, v86
	v_cndmask_b32_e32 v86, 0, v226, vcc
	v_ldexp_f32 v110, v85, v86
	v_add_u32_e32 v85, -4, v147
	v_cvt_f32_u32_e32 v85, v85
	v_mul_f32_e32 v86, v145, v85
	v_cmp_gt_f32_e32 vcc, s96, v86
	s_nop 1
	v_cndmask_b32_e32 v86, 0, v225, vcc
	v_fmac_f32_e32 v86, v145, v85
	v_exp_f32_e32 v85, v86
	v_cndmask_b32_e32 v86, 0, v226, vcc
	v_ldexp_f32 v111, v85, v86
	v_lshlrev_b32_e32 v86, 16, v81
	v_pk_mul_f32 v[112:113], v[108:109], v[86:87]
	v_pk_mul_f32 v[86:87], v[110:111], v[86:87]
	v_cvt_pk_bf16_f32 v81, v112, v113
	v_cvt_pk_bf16_f32 v85, v86, v87
	v_add_u32_e32 v87, 3, v146
	v_cvt_f32_u32_e32 v87, v87
	v_add_u32_e32 v86, -3, v147
	v_cvt_f32_u32_e32 v86, v86
	v_mul_f32_e32 v112, v144, v87
	v_cmp_gt_f32_e32 vcc, s96, v112
	s_nop 1
	v_cndmask_b32_e32 v112, 0, v225, vcc
	v_fmac_f32_e32 v112, v144, v87
	v_exp_f32_e32 v87, v112
	v_cndmask_b32_e32 v112, 0, v226, vcc
	v_ldexp_f32 v112, v87, v112
	v_add_u32_e32 v87, 2, v146
	v_cvt_f32_u32_e32 v87, v87
	v_mul_f32_e32 v113, v144, v87
	v_cmp_gt_f32_e32 vcc, s96, v113
	s_nop 1
	v_cndmask_b32_e32 v113, 0, v225, vcc
	v_fmac_f32_e32 v113, v144, v87
	v_exp_f32_e32 v87, v113
	v_cndmask_b32_e32 v113, 0, v226, vcc
	v_ldexp_f32 v113, v87, v113
	v_mul_f32_e32 v87, v145, v86
	v_cmp_gt_f32_e32 vcc, s96, v87
	s_nop 1
	v_cndmask_b32_e32 v87, 0, v225, vcc
	v_fmac_f32_e32 v87, v145, v86
	v_exp_f32_e32 v86, v87
	v_cndmask_b32_e32 v87, 0, v226, vcc
	v_ldexp_f32 v114, v86, v87
	v_add_u32_e32 v86, -2, v147
	v_cvt_f32_u32_e32 v86, v86
	v_mul_f32_e32 v87, v145, v86
	v_cmp_gt_f32_e32 vcc, s96, v87
	s_nop 1
	v_cndmask_b32_e32 v87, 0, v225, vcc
	v_fmac_f32_e32 v87, v145, v86
	v_exp_f32_e32 v86, v87
	v_cndmask_b32_e32 v87, 0, v226, vcc
	v_ldexp_f32 v115, v86, v87
	v_lshlrev_b32_e32 v86, 16, v82
	v_and_b32_e32 v87, 0xffff0000, v82
	v_pk_mul_f32 v[116:117], v[112:113], v[86:87]
	v_pk_mul_f32 v[86:87], v[114:115], v[86:87]
	v_cvt_pk_bf16_f32 v82, v116, v117
	v_add_u32_e32 v116, 1, v146
	v_cvt_f32_u32_e32 v116, v116
	v_cvt_pk_bf16_f32 v86, v86, v87
	v_add_u32_e32 v87, -1, v147
	v_cvt_f32_u32_e32 v87, v87
	v_mul_f32_e32 v117, v144, v116
	v_cmp_gt_f32_e32 vcc, s96, v117
	s_nop 1
	v_cndmask_b32_e32 v117, 0, v225, vcc
	v_fmac_f32_e32 v117, v144, v116
	v_exp_f32_e32 v116, v117
	v_cndmask_b32_e32 v117, 0, v226, vcc
	v_ldexp_f32 v116, v116, v117
	v_cvt_f32_u32_e32 v117, v146
	v_subrev_u32_e32 v146, 32, v146
	v_mul_f32_e32 v118, v144, v117
	v_cmp_gt_f32_e32 vcc, s96, v118
	s_nop 1
	v_cndmask_b32_e32 v119, 0, v225, vcc
	v_fmac_f32_e32 v119, v144, v117
	v_exp_f32_e32 v117, v119
	v_cndmask_b32_e32 v118, 0, v226, vcc
	v_ldexp_f32 v117, v117, v118
	v_mul_f32_e32 v118, v145, v87
	v_cmp_gt_f32_e32 vcc, s96, v118
	s_nop 1
	v_cndmask_b32_e32 v118, 0, v225, vcc
	v_fmac_f32_e32 v118, v145, v87
	v_exp_f32_e32 v87, v118
	v_cndmask_b32_e32 v118, 0, v226, vcc
	v_ldexp_f32 v118, v87, v118
	v_cvt_f32_u32_e32 v87, v147
	v_add_u32_e32 v147, 32, v147
	v_mul_f32_e32 v119, v145, v87
	v_cmp_gt_f32_e32 vcc, s96, v119
	s_nop 1
	v_cndmask_b32_e32 v148, 0, v225, vcc
	v_fmac_f32_e32 v148, v145, v87
	v_exp_f32_e32 v87, v148
	v_lshlrev_b32_e32 v148, 16, v83
	v_pk_mul_f32 v[150:151], v[116:117], v[148:149]
	v_cndmask_b32_e32 v119, 0, v226, vcc
	v_cvt_pk_bf16_f32 v83, v150, v151
	v_ldexp_f32 v119, v87, v119
	v_pk_mul_f32 v[148:149], v[118:119], v[148:149]
	s_nop 0
	v_mfma_f32_16x16x32_bf16 v[52:55], v[64:67], v[80:83], v[52:55]
	v_cvt_pk_bf16_f32 v87, v148, v149
	s_nop 0
	v_mfma_f32_16x16x32_bf16 v[40:43], v[68:71], v[80:83], v[40:43]
	s_nop 0
	v_mfma_f32_16x16x32_bf16 v[24:27], v[72:75], v[80:83], v[24:27]
	s_nop 0
	v_mfma_f32_16x16x32_bf16 v[8:11], v[76:79], v[80:83], v[8:11]
	v_add_co_u32_e32 v80, vcc, s10, v120
	s_nop 1
	v_addc_co_u32_e32 v81, vcc, 0, v121, vcc
	v_mov_b32_e32 v80, v184
	v_mov_b32_e32 v81, v185
	v_mov_b32_e32 v82, v186
	v_mov_b32_e32 v83, v187
	v_mfma_f32_16x16x32_bf16 v[60:63], v[64:67], v[84:87], v[60:63]
	v_mfma_f32_16x16x32_bf16 v[44:47], v[68:71], v[84:87], v[44:47]
	v_mfma_f32_16x16x32_bf16 v[28:31], v[72:75], v[84:87], v[28:31]
	v_mfma_f32_16x16x32_bf16 v[12:15], v[76:79], v[84:87], v[12:15]
	s_nop 0
	v_lshlrev_b32_e32 v84, 16, v80
	v_and_b32_e32 v85, 0xffff0000, v80
	v_pk_mul_f32 v[86:87], v[104:105], v[84:85]
	v_pk_mul_f32 v[84:85], v[106:107], v[84:85]
	v_cvt_pk_bf16_f32 v80, v86, v87
	v_lshlrev_b32_e32 v86, 16, v81
	v_and_b32_e32 v87, 0xffff0000, v81
	v_pk_mul_f32 v[104:105], v[108:109], v[86:87]
	v_pk_mul_f32 v[86:87], v[110:111], v[86:87]
	v_cvt_pk_bf16_f32 v84, v84, v85
	v_cvt_pk_bf16_f32 v85, v86, v87
	v_lshlrev_b32_e32 v86, 16, v82
	v_and_b32_e32 v87, 0xffff0000, v82
	v_cvt_pk_bf16_f32 v81, v104, v105
	v_pk_mul_f32 v[104:105], v[112:113], v[86:87]
	v_pk_mul_f32 v[86:87], v[114:115], v[86:87]
	v_cvt_pk_bf16_f32 v82, v104, v105
	v_lshlrev_b32_e32 v104, 16, v83
	v_and_b32_e32 v105, 0xffff0000, v83
	v_pk_mul_f32 v[106:107], v[116:117], v[104:105]
	v_pk_mul_f32 v[104:105], v[118:119], v[104:105]
	v_cvt_pk_bf16_f32 v86, v86, v87
	v_cvt_pk_bf16_f32 v83, v106, v107
	v_cvt_pk_bf16_f32 v87, v104, v105
	s_nop 0
	v_mfma_f32_16x16x32_bf16 v[48:51], v[64:67], v[80:83], v[48:51]
	v_mfma_f32_16x16x32_bf16 v[56:59], v[64:67], v[84:87], v[56:59]
	v_mfma_f32_16x16x32_bf16 v[32:35], v[68:71], v[80:83], v[32:35]
	v_mfma_f32_16x16x32_bf16 v[36:39], v[68:71], v[84:87], v[36:39]
	v_mfma_f32_16x16x32_bf16 v[16:19], v[72:75], v[80:83], v[16:19]
	v_mfma_f32_16x16x32_bf16 v[20:23], v[72:75], v[84:87], v[20:23]
	v_mfma_f32_16x16x32_bf16 v[0:3], v[76:79], v[80:83], v[0:3]
	v_mfma_f32_16x16x32_bf16 v[4:7], v[76:79], v[84:87], v[4:7]
	s_cbranch_scc0 .LBB0_471
	v_or_b32_e32 v68, s0, v123
	v_or_b32_e32 v192, v68, v124
	v_lshlrev_b64 v[64:65], 2, v[192:193]
	v_lshl_add_u64 v[66:67], v[96:97], 0, v[64:65]
	v_lshl_add_u64 v[64:65], v[98:99], 0, v[64:65]
	v_add_u32_e32 v192, v68, v124
	global_store_dword v[64:65], v60, off
	v_lshlrev_b64 v[64:65], 2, v[192:193]
	global_store_dword v[66:67], v52, off
	v_lshl_add_u64 v[66:67], v[96:97], 0, v[64:65]
	global_store_dword v[66:67], v53, off offset:256
	v_lshl_add_u64 v[52:53], v[98:99], 0, v[64:65]
	v_add_u32_e32 v192, v68, v127
	global_store_dword v[52:53], v61, off offset:256
	global_store_dword v[66:67], v54, off offset:512
	global_store_dword v[52:53], v62, off offset:512
	global_store_dword v[66:67], v55, off offset:768
	global_store_dword v[52:53], v63, off offset:768
	global_store_dword v[66:67], v48, off offset:64
	global_store_dword v[52:53], v56, off offset:64
	v_lshlrev_b64 v[52:53], 2, v[192:193]
	v_lshl_add_u64 v[54:55], v[96:97], 0, v[52:53]
	global_store_dword v[54:55], v49, off offset:64
	v_lshl_add_u64 v[48:49], v[98:99], 0, v[52:53]
	v_add_u32_e32 v192, v68, v128
	global_store_dword v[48:49], v57, off offset:64
	v_lshlrev_b64 v[48:49], 2, v[192:193]
	v_lshl_add_u64 v[52:53], v[96:97], 0, v[48:49]
	v_lshl_add_u64 v[48:49], v[98:99], 0, v[48:49]
	v_add_u32_e32 v192, v68, v129
	global_store_dword v[48:49], v58, off offset:64
	v_lshlrev_b64 v[48:49], 2, v[192:193]
	global_store_dword v[52:53], v50, off offset:64
	v_lshl_add_u64 v[52:53], v[96:97], 0, v[48:49]
	v_lshl_add_u64 v[48:49], v[98:99], 0, v[48:49]
	v_or_b32_e32 v192, v68, v130
	global_store_dword v[48:49], v59, off offset:64
	v_lshlrev_b64 v[48:49], 2, v[192:193]
	global_store_dword v[52:53], v51, off offset:64
	v_lshl_add_u64 v[50:51], v[96:97], 0, v[48:49]
	v_lshl_add_u64 v[48:49], v[98:99], 0, v[48:49]
	v_or_b32_e32 v192, v68, v131
	global_store_dword v[48:49], v44, off
	v_lshlrev_b64 v[48:49], 2, v[192:193]
	global_store_dword v[50:51], v40, off
	v_lshl_add_u64 v[50:51], v[96:97], 0, v[48:49]
	global_store_dword v[50:51], v41, off
	v_lshl_add_u64 v[40:41], v[98:99], 0, v[48:49]
	v_or_b32_e32 v192, v68, v132
	global_store_dword v[40:41], v45, off
	v_lshlrev_b64 v[40:41], 2, v[192:193]
	v_lshl_add_u64 v[44:45], v[96:97], 0, v[40:41]
	v_lshl_add_u64 v[40:41], v[98:99], 0, v[40:41]
	v_or_b32_e32 v192, v68, v133
	global_store_dword v[40:41], v46, off
	v_lshlrev_b64 v[40:41], 2, v[192:193]
	global_store_dword v[44:45], v42, off
	v_lshl_add_u64 v[44:45], v[96:97], 0, v[40:41]
	v_lshl_add_u64 v[40:41], v[98:99], 0, v[40:41]
	v_add_u32_e32 v192, v68, v130
	global_store_dword v[40:41], v47, off
	v_lshlrev_b64 v[40:41], 2, v[192:193]
	global_store_dword v[44:45], v43, off
	v_lshl_add_u64 v[42:43], v[96:97], 0, v[40:41]
	v_lshl_add_u64 v[40:41], v[98:99], 0, v[40:41]
	v_add_u32_e32 v192, v68, v131
	global_store_dword v[40:41], v36, off offset:64
	v_lshlrev_b64 v[40:41], 2, v[192:193]
	global_store_dword v[42:43], v32, off offset:64
	v_lshl_add_u64 v[42:43], v[96:97], 0, v[40:41]
	global_store_dword v[42:43], v33, off offset:64
	v_lshl_add_u64 v[32:33], v[98:99], 0, v[40:41]
	v_add_u32_e32 v192, v68, v132
	global_store_dword v[32:33], v37, off offset:64
	v_lshlrev_b64 v[32:33], 2, v[192:193]
	v_lshl_add_u64 v[36:37], v[96:97], 0, v[32:33]
	v_lshl_add_u64 v[32:33], v[98:99], 0, v[32:33]
	v_add_u32_e32 v192, v68, v133
	global_store_dword v[32:33], v38, off offset:64
	v_lshlrev_b64 v[32:33], 2, v[192:193]
	global_store_dword v[36:37], v34, off offset:64
	v_lshl_add_u64 v[36:37], v[96:97], 0, v[32:33]
	v_lshl_add_u64 v[32:33], v[98:99], 0, v[32:33]
	v_or_b32_e32 v192, v68, v134
	global_store_dword v[32:33], v39, off offset:64
	v_lshlrev_b64 v[32:33], 2, v[192:193]
	global_store_dword v[36:37], v35, off offset:64
	v_lshl_add_u64 v[34:35], v[96:97], 0, v[32:33]
	v_lshl_add_u64 v[32:33], v[98:99], 0, v[32:33]
	v_or_b32_e32 v192, v68, v135
	global_store_dword v[32:33], v28, off
	v_lshlrev_b64 v[32:33], 2, v[192:193]
	global_store_dword v[34:35], v24, off
	v_lshl_add_u64 v[34:35], v[96:97], 0, v[32:33]
	global_store_dword v[34:35], v25, off
	v_lshl_add_u64 v[24:25], v[98:99], 0, v[32:33]
	v_or_b32_e32 v192, v68, v136
	global_store_dword v[24:25], v29, off
	v_lshlrev_b64 v[24:25], 2, v[192:193]
	v_lshl_add_u64 v[28:29], v[96:97], 0, v[24:25]
	v_lshl_add_u64 v[24:25], v[98:99], 0, v[24:25]
	v_or_b32_e32 v192, v68, v137
	global_store_dword v[24:25], v30, off
	v_lshlrev_b64 v[24:25], 2, v[192:193]
	global_store_dword v[28:29], v26, off
	v_lshl_add_u64 v[28:29], v[96:97], 0, v[24:25]
	v_lshl_add_u64 v[24:25], v[98:99], 0, v[24:25]
	v_add_u32_e32 v192, v68, v134
	global_store_dword v[24:25], v31, off
	v_lshlrev_b64 v[24:25], 2, v[192:193]
	global_store_dword v[28:29], v27, off
	v_lshl_add_u64 v[26:27], v[96:97], 0, v[24:25]
	v_lshl_add_u64 v[24:25], v[98:99], 0, v[24:25]
	v_add_u32_e32 v192, v68, v135
	global_store_dword v[24:25], v20, off offset:64
	v_lshlrev_b64 v[24:25], 2, v[192:193]
	global_store_dword v[26:27], v16, off offset:64
	v_lshl_add_u64 v[26:27], v[96:97], 0, v[24:25]
	global_store_dword v[26:27], v17, off offset:64
	v_lshl_add_u64 v[16:17], v[98:99], 0, v[24:25]
	v_add_u32_e32 v192, v68, v136
	global_store_dword v[16:17], v21, off offset:64
	v_lshlrev_b64 v[16:17], 2, v[192:193]
	v_lshl_add_u64 v[20:21], v[96:97], 0, v[16:17]
	v_lshl_add_u64 v[16:17], v[98:99], 0, v[16:17]
	v_add_u32_e32 v192, v68, v137
	global_store_dword v[16:17], v22, off offset:64
	v_lshlrev_b64 v[16:17], 2, v[192:193]
	global_store_dword v[20:21], v18, off offset:64
	v_lshl_add_u64 v[20:21], v[96:97], 0, v[16:17]
	v_lshl_add_u64 v[16:17], v[98:99], 0, v[16:17]
	v_or_b32_e32 v192, v68, v126
	global_store_dword v[16:17], v23, off offset:64
	v_lshlrev_b64 v[16:17], 2, v[192:193]
	global_store_dword v[20:21], v19, off offset:64
	v_lshl_add_u64 v[18:19], v[96:97], 0, v[16:17]
	v_lshl_add_u64 v[16:17], v[98:99], 0, v[16:17]
	v_or_b32_e32 v192, v68, v138
	global_store_dword v[16:17], v12, off
	v_lshlrev_b64 v[16:17], 2, v[192:193]
	global_store_dword v[18:19], v8, off
	v_lshl_add_u64 v[18:19], v[96:97], 0, v[16:17]
	global_store_dword v[18:19], v9, off
	v_lshl_add_u64 v[8:9], v[98:99], 0, v[16:17]
	v_or_b32_e32 v192, v68, v139
	global_store_dword v[8:9], v13, off
	v_lshlrev_b64 v[8:9], 2, v[192:193]
	v_lshl_add_u64 v[12:13], v[96:97], 0, v[8:9]
	v_lshl_add_u64 v[8:9], v[98:99], 0, v[8:9]
	v_or_b32_e32 v192, v68, v140
	global_store_dword v[8:9], v14, off
	v_lshlrev_b64 v[8:9], 2, v[192:193]
	global_store_dword v[12:13], v10, off
	v_lshl_add_u64 v[12:13], v[96:97], 0, v[8:9]
	v_lshl_add_u64 v[8:9], v[98:99], 0, v[8:9]
	v_add_u32_e32 v192, v68, v126
	global_store_dword v[8:9], v15, off
	v_lshlrev_b64 v[8:9], 2, v[192:193]
	global_store_dword v[12:13], v11, off
	v_lshl_add_u64 v[10:11], v[96:97], 0, v[8:9]
	v_lshl_add_u64 v[8:9], v[98:99], 0, v[8:9]
	v_add_u32_e32 v192, v68, v138
	global_store_dword v[8:9], v4, off offset:64
	v_lshlrev_b64 v[8:9], 2, v[192:193]
	global_store_dword v[10:11], v0, off offset:64
	v_lshl_add_u64 v[10:11], v[96:97], 0, v[8:9]
	global_store_dword v[10:11], v1, off offset:64
	v_lshl_add_u64 v[0:1], v[98:99], 0, v[8:9]
	v_add_u32_e32 v192, v68, v139
	global_store_dword v[0:1], v5, off offset:64
	v_lshlrev_b64 v[0:1], 2, v[192:193]
	v_lshl_add_u64 v[4:5], v[96:97], 0, v[0:1]
	v_lshl_add_u64 v[0:1], v[98:99], 0, v[0:1]
	v_add_u32_e32 v192, v68, v140
	global_store_dword v[0:1], v6, off offset:64
	v_lshlrev_b64 v[0:1], 2, v[192:193]
	global_store_dword v[4:5], v2, off offset:64
	v_lshl_add_u64 v[4:5], v[96:97], 0, v[0:1]
	v_lshl_add_u64 v[0:1], v[98:99], 0, v[0:1]
	s_mov_b32 s0, 32
	s_mov_b64 s[8:9], 0
	s_and_b64 vcc, exec, s[6:7]
	global_store_dword v[4:5], v3, off offset:64
	global_store_dword v[0:1], v7, off offset:64
	s_cbranch_vccz .LBB0_470
	s_cmp_lg_u32 s101, 0
	s_cbranch_scc1 .Lru_done
	v_readlane_b32 s0, v253, 5
	v_readfirstlane_b32 s98, v195
	s_nop 1
	s_lshr_b32 s98, s98, 6
	s_sub_i32 s0, s0, 0x80
	s_cmp_lt_u32 s0, 0x80
	s_cbranch_scc0 .Lru_done
	s_and_b32 s99, s98, 3
	s_lshl_b32 s0, s0, 2
	s_add_i32 s0, s0, s99
	s_addk_i32 s0, 0x800
	v_mov_b32_e32 v122, s0
	s_lshl_b32 s0, s0, 5
	v_mov_b32_e32 v143, s0
	s_lshr_b32 s98, s98, 2
	s_and_b32 s98, s98, 1
	s_lshl_b32 s98, s98, 5
	s_or_b32 s101, s98, 0x100
	s_branch .LBB0_469

.LBB0_672:
	v_mov_b32_e32 v4, s10
	v_cndmask_b32_e32 v4, v36, v4, vcc
	v_add_u32_e32 v4, v4, v33
	v_lshl_or_b32 v4, v4, 2, v31
	v_ashrrev_i32_e32 v5, 31, v4
	v_lshlrev_b64 v[6:7], 15, v[4:5]
	v_lshl_add_u64 v[6:7], v[0:1], 0, v[6:7]
	s_add_i32 s2, s10, 1
	s_xor_b32 s3, s10, 0x3ffffffe
	global_load_dword v39, v[6:7], off
	v_add_u32_e32 v6, s3, v32
	v_mov_b32_e32 v7, s2
	v_cndmask_b32_e32 v6, v6, v7, vcc
	v_add_u32_e32 v6, v6, v33
	v_lshl_or_b32 v6, v6, 2, v31
	v_ashrrev_i32_e32 v7, 31, v6
	v_lshlrev_b64 v[8:9], 15, v[6:7]
	v_lshl_add_u64 v[8:9], v[0:1], 0, v[8:9]
	s_add_i32 s2, s10, 2
	s_xor_b32 s3, s10, 0x3ffffffd
	global_load_dword v40, v[8:9], off
	v_add_u32_e32 v8, s3, v32
	v_mov_b32_e32 v9, s2
	v_cndmask_b32_e32 v8, v8, v9, vcc
	v_add_u32_e32 v8, v8, v33
	v_lshl_or_b32 v8, v8, 2, v31
	v_ashrrev_i32_e32 v9, 31, v8
	v_lshlrev_b64 v[10:11], 15, v[8:9]
	v_lshl_add_u64 v[10:11], v[0:1], 0, v[10:11]
	s_add_i32 s2, s10, 3
	s_xor_b32 s3, s10, 0x3ffffffc
	global_load_dword v41, v[10:11], off
	v_add_u32_e32 v10, s3, v32
	v_mov_b32_e32 v11, s2
	v_cndmask_b32_e32 v10, v10, v11, vcc
	v_add_u32_e32 v10, v10, v33
	v_lshl_or_b32 v10, v10, 2, v31
	v_ashrrev_i32_e32 v11, 31, v10
	v_lshlrev_b64 v[12:13], 15, v[10:11]
	v_lshl_add_u64 v[12:13], v[0:1], 0, v[12:13]
	s_add_i32 s2, s10, 4
	s_xor_b32 s3, s10, 0x3ffffffb
	global_load_dword v42, v[12:13], off
	v_add_u32_e32 v12, s3, v32
	v_mov_b32_e32 v13, s2
	v_cndmask_b32_e32 v12, v12, v13, vcc
	v_add_u32_e32 v12, v12, v33
	v_lshl_or_b32 v12, v12, 2, v31
	v_ashrrev_i32_e32 v13, 31, v12
	v_lshlrev_b64 v[14:15], 15, v[12:13]
	v_lshl_add_u64 v[14:15], v[0:1], 0, v[14:15]
	s_add_i32 s2, s10, 5
	s_xor_b32 s3, s10, 0x3ffffffa
	global_load_dword v43, v[14:15], off
	v_add_u32_e32 v14, s3, v32
	v_mov_b32_e32 v15, s2
	v_cndmask_b32_e32 v14, v14, v15, vcc
	v_add_u32_e32 v14, v14, v33
	v_lshl_or_b32 v14, v14, 2, v31
	v_ashrrev_i32_e32 v15, 31, v14
	v_lshlrev_b64 v[16:17], 15, v[14:15]
	v_lshl_add_u64 v[16:17], v[0:1], 0, v[16:17]
	s_add_i32 s2, s10, 6
	s_xor_b32 s3, s10, 0x3ffffff9
	global_load_dword v44, v[16:17], off
	v_add_u32_e32 v16, s3, v32
	v_mov_b32_e32 v17, s2
	v_cndmask_b32_e32 v16, v16, v17, vcc
	v_add_u32_e32 v16, v16, v33
	v_lshl_or_b32 v16, v16, 2, v31
	v_ashrrev_i32_e32 v17, 31, v16
	v_lshlrev_b64 v[18:19], 15, v[16:17]
	v_lshl_add_u64 v[18:19], v[0:1], 0, v[18:19]
	s_add_i32 s2, s10, 7
	s_xor_b32 s3, s10, 0x3ffffff8
	global_load_dword v45, v[18:19], off
	v_add_u32_e32 v18, s3, v32
	v_mov_b32_e32 v19, s2
	v_cndmask_b32_e32 v18, v18, v19, vcc
	v_add_u32_e32 v18, v18, v33
	v_lshl_or_b32 v18, v18, 2, v31
	v_ashrrev_i32_e32 v19, 31, v18
	v_lshlrev_b64 v[20:21], 15, v[18:19]
	v_lshl_add_u64 v[20:21], v[0:1], 0, v[20:21]
	s_add_i32 s2, s10, 8
	s_xor_b32 s3, s10, 0x3ffffff7
	global_load_dword v54, v[20:21], off
	v_add_u32_e32 v20, s3, v32
	v_mov_b32_e32 v21, s2
	v_cndmask_b32_e32 v20, v20, v21, vcc
	v_add_u32_e32 v20, v20, v33
	v_lshl_or_b32 v20, v20, 2, v31
	v_ashrrev_i32_e32 v21, 31, v20
	v_lshlrev_b64 v[22:23], 15, v[20:21]
	v_lshl_add_u64 v[22:23], v[0:1], 0, v[22:23]
	s_add_i32 s2, s10, 9
	s_xor_b32 s3, s10, 0x3ffffff6
	global_load_dword v55, v[22:23], off
	v_add_u32_e32 v22, s3, v32
	v_mov_b32_e32 v23, s2
	v_cndmask_b32_e32 v22, v22, v23, vcc
	v_add_u32_e32 v22, v22, v33
	v_lshl_or_b32 v22, v22, 2, v31
	v_ashrrev_i32_e32 v23, 31, v22
	v_lshlrev_b64 v[24:25], 15, v[22:23]
	v_lshl_add_u64 v[24:25], v[0:1], 0, v[24:25]
	s_add_i32 s2, s10, 10
	s_xor_b32 s3, s10, 0x3ffffff5
	global_load_dword v56, v[24:25], off
	v_add_u32_e32 v24, s3, v32
	v_mov_b32_e32 v25, s2
	v_cndmask_b32_e32 v24, v24, v25, vcc
	v_add_u32_e32 v24, v24, v33
	v_lshl_or_b32 v24, v24, 2, v31
	v_ashrrev_i32_e32 v25, 31, v24
	v_lshlrev_b64 v[26:27], 15, v[24:25]
	v_lshl_add_u64 v[26:27], v[0:1], 0, v[26:27]
	s_add_i32 s2, s10, 11
	s_xor_b32 s3, s10, 0x3ffffff4
	global_load_dword v57, v[26:27], off
	v_add_u32_e32 v26, s3, v32
	v_mov_b32_e32 v27, s2
	v_cndmask_b32_e32 v26, v26, v27, vcc
	v_add_u32_e32 v26, v26, v33
	v_lshl_or_b32 v26, v26, 2, v31
	v_ashrrev_i32_e32 v27, 31, v26
	v_lshlrev_b64 v[28:29], 15, v[26:27]
	v_lshl_add_u64 v[28:29], v[0:1], 0, v[28:29]
	s_add_i32 s2, s10, 12
	s_xor_b32 s3, s10, 0x3ffffff3
	global_load_dword v58, v[28:29], off
	v_add_u32_e32 v28, s3, v32
	v_mov_b32_e32 v29, s2
	v_cndmask_b32_e32 v28, v28, v29, vcc
	v_add_u32_e32 v28, v28, v33
	v_lshl_or_b32 v28, v28, 2, v31
	v_ashrrev_i32_e32 v29, 31, v28
	v_lshlrev_b64 v[46:47], 15, v[28:29]
	v_lshl_add_u64 v[46:47], v[0:1], 0, v[46:47]
	s_add_i32 s2, s10, 13
	s_xor_b32 s3, s10, 0x3ffffff2
	global_load_dword v59, v[46:47], off
	v_add_u32_e32 v38, s3, v32
	v_mov_b32_e32 v46, s2
	v_cndmask_b32_e32 v38, v38, v46, vcc
	v_add_u32_e32 v38, v38, v33
	v_lshl_or_b32 v46, v38, 2, v31
	v_ashrrev_i32_e32 v47, 31, v46
	v_lshlrev_b64 v[48:49], 15, v[46:47]
	v_lshl_add_u64 v[48:49], v[0:1], 0, v[48:49]
	s_add_i32 s2, s10, 14
	s_xor_b32 s3, s10, 0x3ffffff1
	global_load_dword v60, v[48:49], off
	v_add_u32_e32 v38, s3, v32
	v_mov_b32_e32 v48, s2
	v_cndmask_b32_e32 v38, v38, v48, vcc
	v_add_u32_e32 v38, v38, v33
	v_lshl_or_b32 v48, v38, 2, v31
	v_ashrrev_i32_e32 v49, 31, v48
	v_lshlrev_b64 v[50:51], 15, v[48:49]
	v_lshl_add_u64 v[50:51], v[0:1], 0, v[50:51]
	s_add_i32 s2, s10, 15
	s_xor_b32 s3, s10, 0x3ffffff0
	global_load_dword v61, v[50:51], off
	v_add_u32_e32 v38, s3, v32
	v_mov_b32_e32 v50, s2
	v_cndmask_b32_e32 v38, v38, v50, vcc
	v_add_u32_e32 v38, v38, v33
	v_lshl_or_b32 v50, v38, 2, v31
	v_ashrrev_i32_e32 v51, 31, v50
	v_lshlrev_b64 v[52:53], 15, v[50:51]
	v_lshl_add_u64 v[52:53], v[0:1], 0, v[52:53]
	global_load_dword v38, v[52:53], off
	s_add_i32 s10, s10, 16
	v_add_u32_e32 v36, -16, v36
	v_mov_b32_e32 v64, s10
	v_cndmask_b32_e32 v64, v36, v64, vcc
	v_add_u32_e32 v64, v64, v33
	v_lshl_or_b32 v64, v64, 2, v31
	v_ashrrev_i32_e32 v65, 31, v64
	v_lshlrev_b64 v[66:67], 15, v[64:65]
	v_lshl_add_u64 v[66:67], v[0:1], 0, v[66:67]
	s_add_i32 s2, s10, 1
	s_xor_b32 s3, s10, 0x3ffffffe
	global_load_dword v99, v[66:67], off
	v_add_u32_e32 v66, s3, v32
	v_mov_b32_e32 v67, s2
	v_cndmask_b32_e32 v66, v66, v67, vcc
	v_add_u32_e32 v66, v66, v33
	v_lshl_or_b32 v66, v66, 2, v31
	v_ashrrev_i32_e32 v67, 31, v66
	v_lshlrev_b64 v[68:69], 15, v[66:67]
	v_lshl_add_u64 v[68:69], v[0:1], 0, v[68:69]
	s_add_i32 s2, s10, 2
	s_xor_b32 s3, s10, 0x3ffffffd
	global_load_dword v100, v[68:69], off
	v_add_u32_e32 v68, s3, v32
	v_mov_b32_e32 v69, s2
	v_cndmask_b32_e32 v68, v68, v69, vcc
	v_add_u32_e32 v68, v68, v33
	v_lshl_or_b32 v68, v68, 2, v31
	v_ashrrev_i32_e32 v69, 31, v68
	v_lshlrev_b64 v[70:71], 15, v[68:69]
	v_lshl_add_u64 v[70:71], v[0:1], 0, v[70:71]
	s_add_i32 s2, s10, 3
	s_xor_b32 s3, s10, 0x3ffffffc
	global_load_dword v101, v[70:71], off
	v_add_u32_e32 v70, s3, v32
	v_mov_b32_e32 v71, s2
	v_cndmask_b32_e32 v70, v70, v71, vcc
	v_add_u32_e32 v70, v70, v33
	v_lshl_or_b32 v70, v70, 2, v31
	v_ashrrev_i32_e32 v71, 31, v70
	v_lshlrev_b64 v[72:73], 15, v[70:71]
	v_lshl_add_u64 v[72:73], v[0:1], 0, v[72:73]
	s_add_i32 s2, s10, 4
	s_xor_b32 s3, s10, 0x3ffffffb
	global_load_dword v102, v[72:73], off
	v_add_u32_e32 v72, s3, v32
	v_mov_b32_e32 v73, s2
	v_cndmask_b32_e32 v72, v72, v73, vcc
	v_add_u32_e32 v72, v72, v33
	v_lshl_or_b32 v72, v72, 2, v31
	v_ashrrev_i32_e32 v73, 31, v72
	v_lshlrev_b64 v[74:75], 15, v[72:73]
	v_lshl_add_u64 v[74:75], v[0:1], 0, v[74:75]
	s_add_i32 s2, s10, 5
	s_xor_b32 s3, s10, 0x3ffffffa
	global_load_dword v103, v[74:75], off
	v_add_u32_e32 v74, s3, v32
	v_mov_b32_e32 v75, s2
	v_cndmask_b32_e32 v74, v74, v75, vcc
	v_add_u32_e32 v74, v74, v33
	v_lshl_or_b32 v74, v74, 2, v31
	v_ashrrev_i32_e32 v75, 31, v74
	v_lshlrev_b64 v[76:77], 15, v[74:75]
	v_lshl_add_u64 v[76:77], v[0:1], 0, v[76:77]
	s_add_i32 s2, s10, 6
	s_xor_b32 s3, s10, 0x3ffffff9
	global_load_dword v104, v[76:77], off
	v_add_u32_e32 v76, s3, v32
	v_mov_b32_e32 v77, s2
	v_cndmask_b32_e32 v76, v76, v77, vcc
	v_add_u32_e32 v76, v76, v33
	v_lshl_or_b32 v76, v76, 2, v31
	v_ashrrev_i32_e32 v77, 31, v76
	v_lshlrev_b64 v[78:79], 15, v[76:77]
	v_lshl_add_u64 v[78:79], v[0:1], 0, v[78:79]
	s_add_i32 s2, s10, 7
	s_xor_b32 s3, s10, 0x3ffffff8
	global_load_dword v105, v[78:79], off
	v_add_u32_e32 v78, s3, v32
	v_mov_b32_e32 v79, s2
	v_cndmask_b32_e32 v78, v78, v79, vcc
	v_add_u32_e32 v78, v78, v33
	v_lshl_or_b32 v78, v78, 2, v31
	v_ashrrev_i32_e32 v79, 31, v78
	v_lshlrev_b64 v[80:81], 15, v[78:79]
	v_lshl_add_u64 v[80:81], v[0:1], 0, v[80:81]
	s_add_i32 s2, s10, 8
	s_xor_b32 s3, s10, 0x3ffffff7
	global_load_dword v114, v[80:81], off
	v_add_u32_e32 v80, s3, v32
	v_mov_b32_e32 v81, s2
	v_cndmask_b32_e32 v80, v80, v81, vcc
	v_add_u32_e32 v80, v80, v33
	v_lshl_or_b32 v80, v80, 2, v31
	v_ashrrev_i32_e32 v81, 31, v80
	v_lshlrev_b64 v[82:83], 15, v[80:81]
	v_lshl_add_u64 v[82:83], v[0:1], 0, v[82:83]
	s_add_i32 s2, s10, 9
	s_xor_b32 s3, s10, 0x3ffffff6
	global_load_dword v115, v[82:83], off
	v_add_u32_e32 v82, s3, v32
	v_mov_b32_e32 v83, s2
	v_cndmask_b32_e32 v82, v82, v83, vcc
	v_add_u32_e32 v82, v82, v33
	v_lshl_or_b32 v82, v82, 2, v31
	v_ashrrev_i32_e32 v83, 31, v82
	v_lshlrev_b64 v[84:85], 15, v[82:83]
	v_lshl_add_u64 v[84:85], v[0:1], 0, v[84:85]
	s_add_i32 s2, s10, 10
	s_xor_b32 s3, s10, 0x3ffffff5
	global_load_dword v116, v[84:85], off
	v_add_u32_e32 v84, s3, v32
	v_mov_b32_e32 v85, s2
	v_cndmask_b32_e32 v84, v84, v85, vcc
	v_add_u32_e32 v84, v84, v33
	v_lshl_or_b32 v84, v84, 2, v31
	v_ashrrev_i32_e32 v85, 31, v84
	v_lshlrev_b64 v[86:87], 15, v[84:85]
	v_lshl_add_u64 v[86:87], v[0:1], 0, v[86:87]
	s_add_i32 s2, s10, 11
	s_xor_b32 s3, s10, 0x3ffffff4
	global_load_dword v117, v[86:87], off
	v_add_u32_e32 v86, s3, v32
	v_mov_b32_e32 v87, s2
	v_cndmask_b32_e32 v86, v86, v87, vcc
	v_add_u32_e32 v86, v86, v33
	v_lshl_or_b32 v86, v86, 2, v31
	v_ashrrev_i32_e32 v87, 31, v86
	v_lshlrev_b64 v[88:89], 15, v[86:87]
	v_lshl_add_u64 v[88:89], v[0:1], 0, v[88:89]
	s_add_i32 s2, s10, 12
	s_xor_b32 s3, s10, 0x3ffffff3
	global_load_dword v118, v[88:89], off
	v_add_u32_e32 v88, s3, v32
	v_mov_b32_e32 v89, s2
	v_cndmask_b32_e32 v88, v88, v89, vcc
	v_add_u32_e32 v88, v88, v33
	v_lshl_or_b32 v88, v88, 2, v31
	v_ashrrev_i32_e32 v89, 31, v88
	v_lshlrev_b64 v[106:107], 15, v[88:89]
	v_lshl_add_u64 v[106:107], v[0:1], 0, v[106:107]
	s_add_i32 s2, s10, 13
	s_xor_b32 s3, s10, 0x3ffffff2
	global_load_dword v119, v[106:107], off
	v_add_u32_e32 v98, s3, v32
	v_mov_b32_e32 v106, s2
	v_cndmask_b32_e32 v98, v98, v106, vcc
	v_add_u32_e32 v98, v98, v33
	v_lshl_or_b32 v106, v98, 2, v31
	v_ashrrev_i32_e32 v107, 31, v106
	v_lshlrev_b64 v[108:109], 15, v[106:107]
	v_lshl_add_u64 v[108:109], v[0:1], 0, v[108:109]
	s_add_i32 s2, s10, 14
	s_xor_b32 s3, s10, 0x3ffffff1
	global_load_dword v120, v[108:109], off
	v_add_u32_e32 v98, s3, v32
	v_mov_b32_e32 v108, s2
	v_cndmask_b32_e32 v98, v98, v108, vcc
	v_add_u32_e32 v98, v98, v33
	v_lshl_or_b32 v108, v98, 2, v31
	v_ashrrev_i32_e32 v109, 31, v108
	v_lshlrev_b64 v[110:111], 15, v[108:109]
	v_lshl_add_u64 v[110:111], v[0:1], 0, v[110:111]
	s_add_i32 s2, s10, 15
	s_xor_b32 s3, s10, 0x3ffffff0
	global_load_dword v121, v[110:111], off
	v_add_u32_e32 v98, s3, v32
	v_mov_b32_e32 v110, s2
	v_cndmask_b32_e32 v98, v98, v110, vcc
	v_add_u32_e32 v98, v98, v33
	v_lshl_or_b32 v110, v98, 2, v31
	v_ashrrev_i32_e32 v111, 31, v110
	v_lshlrev_b64 v[112:113], 15, v[110:111]
	v_lshl_add_u64 v[112:113], v[0:1], 0, v[112:113]
	global_load_dword v98, v[112:113], off
	v_bfe_u32 v52, v37, 16, 1
	v_lshlrev_b64 v[4:5], 14, v[4:5]
	v_add3_u32 v52, v37, v52, s33
	v_lshl_add_u64 v[4:5], v[2:3], 0, v[4:5]
	s_waitcnt vmcnt(31)
	v_fmac_f32_e32 v39, v34, v37
	global_store_short_d16_hi v[4:5], v52, off
	v_bfe_u32 v4, v39, 16, 1
	v_add3_u32 v37, v39, v4, s33
	v_lshlrev_b64 v[4:5], 14, v[6:7]
	v_lshl_add_u64 v[4:5], v[2:3], 0, v[4:5]
	s_waitcnt vmcnt(31)
	v_fmac_f32_e32 v40, v34, v39
	global_store_short_d16_hi v[4:5], v37, off
	v_bfe_u32 v4, v40, 16, 1
	v_add3_u32 v6, v40, v4, s33
	v_lshlrev_b64 v[4:5], 14, v[8:9]
	v_lshl_add_u64 v[4:5], v[2:3], 0, v[4:5]
	s_waitcnt vmcnt(31)
	v_fmac_f32_e32 v41, v34, v40
	global_store_short_d16_hi v[4:5], v6, off
	v_bfe_u32 v4, v41, 16, 1
	v_add3_u32 v6, v41, v4, s33
	v_lshlrev_b64 v[4:5], 14, v[10:11]
	v_lshl_add_u64 v[4:5], v[2:3], 0, v[4:5]
	s_waitcnt vmcnt(31)
	v_fmac_f32_e32 v42, v34, v41
	global_store_short_d16_hi v[4:5], v6, off
	v_bfe_u32 v4, v42, 16, 1
	v_add3_u32 v6, v42, v4, s33
	v_lshlrev_b64 v[4:5], 14, v[12:13]
	v_lshl_add_u64 v[4:5], v[2:3], 0, v[4:5]
	s_waitcnt vmcnt(31)
	v_fmac_f32_e32 v43, v34, v42
	global_store_short_d16_hi v[4:5], v6, off
	v_bfe_u32 v4, v43, 16, 1
	v_add3_u32 v6, v43, v4, s33
	v_lshlrev_b64 v[4:5], 14, v[14:15]
	v_lshl_add_u64 v[4:5], v[2:3], 0, v[4:5]
	s_waitcnt vmcnt(31)
	v_fmac_f32_e32 v44, v34, v43
	global_store_short_d16_hi v[4:5], v6, off
	v_bfe_u32 v4, v44, 16, 1
	v_add3_u32 v6, v44, v4, s33
	v_lshlrev_b64 v[4:5], 14, v[16:17]
	v_lshl_add_u64 v[4:5], v[2:3], 0, v[4:5]
	s_waitcnt vmcnt(31)
	v_fmac_f32_e32 v45, v34, v44
	global_store_short_d16_hi v[4:5], v6, off
	v_bfe_u32 v4, v45, 16, 1
	v_add3_u32 v6, v45, v4, s33
	v_lshlrev_b64 v[4:5], 14, v[18:19]
	v_lshl_add_u64 v[4:5], v[2:3], 0, v[4:5]
	s_waitcnt vmcnt(31)
	v_fmac_f32_e32 v54, v34, v45
	global_store_short_d16_hi v[4:5], v6, off
	v_bfe_u32 v4, v54, 16, 1
	v_add3_u32 v6, v54, v4, s33
	v_lshlrev_b64 v[4:5], 14, v[20:21]
	v_lshl_add_u64 v[4:5], v[2:3], 0, v[4:5]
	s_waitcnt vmcnt(31)
	v_fmac_f32_e32 v55, v34, v54
	global_store_short_d16_hi v[4:5], v6, off
	v_bfe_u32 v4, v55, 16, 1
	v_add3_u32 v6, v55, v4, s33
	v_lshlrev_b64 v[4:5], 14, v[22:23]
	v_lshl_add_u64 v[4:5], v[2:3], 0, v[4:5]
	s_waitcnt vmcnt(31)
	v_fmac_f32_e32 v56, v34, v55
	global_store_short_d16_hi v[4:5], v6, off
	v_bfe_u32 v4, v56, 16, 1
	v_add3_u32 v6, v56, v4, s33
	v_lshlrev_b64 v[4:5], 14, v[24:25]
	v_lshl_add_u64 v[4:5], v[2:3], 0, v[4:5]
	s_waitcnt vmcnt(31)
	v_fmac_f32_e32 v57, v34, v56
	global_store_short_d16_hi v[4:5], v6, off
	v_bfe_u32 v4, v57, 16, 1
	v_add3_u32 v6, v57, v4, s33
	v_lshlrev_b64 v[4:5], 14, v[26:27]
	v_lshl_add_u64 v[4:5], v[2:3], 0, v[4:5]
	s_waitcnt vmcnt(31)
	v_fmac_f32_e32 v58, v34, v57
	global_store_short_d16_hi v[4:5], v6, off
	v_bfe_u32 v4, v58, 16, 1
	v_add3_u32 v6, v58, v4, s33
	v_lshlrev_b64 v[4:5], 14, v[28:29]
	v_lshl_add_u64 v[4:5], v[2:3], 0, v[4:5]
	s_waitcnt vmcnt(31)
	v_fmac_f32_e32 v59, v34, v58
	global_store_short_d16_hi v[4:5], v6, off
	v_bfe_u32 v4, v59, 16, 1
	v_add3_u32 v6, v59, v4, s33
	v_lshlrev_b64 v[4:5], 14, v[46:47]
	v_lshl_add_u64 v[4:5], v[2:3], 0, v[4:5]
	s_waitcnt vmcnt(31)
	v_fmac_f32_e32 v60, v34, v59
	global_store_short_d16_hi v[4:5], v6, off
	v_bfe_u32 v4, v60, 16, 1
	v_add3_u32 v6, v60, v4, s33
	v_lshlrev_b64 v[4:5], 14, v[48:49]
	v_lshl_add_u64 v[4:5], v[2:3], 0, v[4:5]
	s_waitcnt vmcnt(31)
	v_fmac_f32_e32 v61, v34, v60
	global_store_short_d16_hi v[4:5], v6, off
	v_bfe_u32 v4, v61, 16, 1
	v_add_u32_e32 v35, -1, v35
	v_add3_u32 v6, v61, v4, s33
	v_lshlrev_b64 v[4:5], 14, v[50:51]
	s_waitcnt vmcnt(31)
	v_fmac_f32_e32 v38, v34, v61
	v_lshl_add_u64 v[4:5], v[2:3], 0, v[4:5]
	v_mov_b32_e32 v97, v38
	global_store_short_d16_hi v[4:5], v6, off
	v_bfe_u32 v112, v97, 16, 1
	v_lshlrev_b64 v[64:65], 14, v[64:65]
	v_add3_u32 v112, v97, v112, s33
	v_lshl_add_u64 v[64:65], v[2:3], 0, v[64:65]
	s_waitcnt vmcnt(31)
	v_fmac_f32_e32 v99, v34, v97
	global_store_short_d16_hi v[64:65], v112, off
	v_bfe_u32 v64, v99, 16, 1
	v_add3_u32 v97, v99, v64, s33
	v_lshlrev_b64 v[64:65], 14, v[66:67]
	v_lshl_add_u64 v[64:65], v[2:3], 0, v[64:65]
	s_waitcnt vmcnt(31)
	v_fmac_f32_e32 v100, v34, v99
	global_store_short_d16_hi v[64:65], v97, off
	v_bfe_u32 v64, v100, 16, 1
	v_add3_u32 v66, v100, v64, s33
	v_lshlrev_b64 v[64:65], 14, v[68:69]
	v_lshl_add_u64 v[64:65], v[2:3], 0, v[64:65]
	s_waitcnt vmcnt(31)
	v_fmac_f32_e32 v101, v34, v100
	global_store_short_d16_hi v[64:65], v66, off
	v_bfe_u32 v64, v101, 16, 1
	v_add3_u32 v66, v101, v64, s33
	v_lshlrev_b64 v[64:65], 14, v[70:71]
	v_lshl_add_u64 v[64:65], v[2:3], 0, v[64:65]
	s_waitcnt vmcnt(31)
	v_fmac_f32_e32 v102, v34, v101
	global_store_short_d16_hi v[64:65], v66, off
	v_bfe_u32 v64, v102, 16, 1
	v_add3_u32 v66, v102, v64, s33
	v_lshlrev_b64 v[64:65], 14, v[72:73]
	v_lshl_add_u64 v[64:65], v[2:3], 0, v[64:65]
	s_waitcnt vmcnt(31)
	v_fmac_f32_e32 v103, v34, v102
	global_store_short_d16_hi v[64:65], v66, off
	v_bfe_u32 v64, v103, 16, 1
	v_add3_u32 v66, v103, v64, s33
	v_lshlrev_b64 v[64:65], 14, v[74:75]
	v_lshl_add_u64 v[64:65], v[2:3], 0, v[64:65]
	s_waitcnt vmcnt(31)
	v_fmac_f32_e32 v104, v34, v103
	global_store_short_d16_hi v[64:65], v66, off
	v_bfe_u32 v64, v104, 16, 1
	v_add3_u32 v66, v104, v64, s33
	v_lshlrev_b64 v[64:65], 14, v[76:77]
	v_lshl_add_u64 v[64:65], v[2:3], 0, v[64:65]
	s_waitcnt vmcnt(31)
	v_fmac_f32_e32 v105, v34, v104
	global_store_short_d16_hi v[64:65], v66, off
	v_bfe_u32 v64, v105, 16, 1
	v_add3_u32 v66, v105, v64, s33
	v_lshlrev_b64 v[64:65], 14, v[78:79]
	v_lshl_add_u64 v[64:65], v[2:3], 0, v[64:65]
	s_waitcnt vmcnt(31)
	v_fmac_f32_e32 v114, v34, v105
	global_store_short_d16_hi v[64:65], v66, off
	v_bfe_u32 v64, v114, 16, 1
	v_add3_u32 v66, v114, v64, s33
	v_lshlrev_b64 v[64:65], 14, v[80:81]
	v_lshl_add_u64 v[64:65], v[2:3], 0, v[64:65]
	s_waitcnt vmcnt(31)
	v_fmac_f32_e32 v115, v34, v114
	global_store_short_d16_hi v[64:65], v66, off
	v_bfe_u32 v64, v115, 16, 1
	v_add3_u32 v66, v115, v64, s33
	v_lshlrev_b64 v[64:65], 14, v[82:83]
	v_lshl_add_u64 v[64:65], v[2:3], 0, v[64:65]
	s_waitcnt vmcnt(31)
	v_fmac_f32_e32 v116, v34, v115
	global_store_short_d16_hi v[64:65], v66, off
	v_bfe_u32 v64, v116, 16, 1
	v_add3_u32 v66, v116, v64, s33
	v_lshlrev_b64 v[64:65], 14, v[84:85]
	v_lshl_add_u64 v[64:65], v[2:3], 0, v[64:65]
	s_waitcnt vmcnt(31)
	v_fmac_f32_e32 v117, v34, v116
	global_store_short_d16_hi v[64:65], v66, off
	v_bfe_u32 v64, v117, 16, 1
	v_add3_u32 v66, v117, v64, s33
	v_lshlrev_b64 v[64:65], 14, v[86:87]
	v_lshl_add_u64 v[64:65], v[2:3], 0, v[64:65]
	s_waitcnt vmcnt(31)
	v_fmac_f32_e32 v118, v34, v117
	global_store_short_d16_hi v[64:65], v66, off
	v_bfe_u32 v64, v118, 16, 1
	v_add3_u32 v66, v118, v64, s33
	v_lshlrev_b64 v[64:65], 14, v[88:89]
	v_lshl_add_u64 v[64:65], v[2:3], 0, v[64:65]
	s_waitcnt vmcnt(31)
	v_fmac_f32_e32 v119, v34, v118
	global_store_short_d16_hi v[64:65], v66, off
	v_bfe_u32 v64, v119, 16, 1
	v_add3_u32 v66, v119, v64, s33
	v_lshlrev_b64 v[64:65], 14, v[106:107]
	v_lshl_add_u64 v[64:65], v[2:3], 0, v[64:65]
	s_waitcnt vmcnt(31)
	v_fmac_f32_e32 v120, v34, v119
	global_store_short_d16_hi v[64:65], v66, off
	v_bfe_u32 v64, v120, 16, 1
	v_add3_u32 v66, v120, v64, s33
	v_lshlrev_b64 v[64:65], 14, v[108:109]
	v_lshl_add_u64 v[64:65], v[2:3], 0, v[64:65]
	s_waitcnt vmcnt(31)
	v_fmac_f32_e32 v121, v34, v120
	global_store_short_d16_hi v[64:65], v66, off
	v_bfe_u32 v64, v121, 16, 1
	v_add_u32_e32 v35, -1, v35
	v_add3_u32 v66, v121, v64, s33
	v_lshlrev_b64 v[64:65], 14, v[110:111]
	s_waitcnt vmcnt(31)
	v_fmac_f32_e32 v98, v34, v121
	s_add_i32 s10, s10, 16
	v_cmp_eq_u32_e64 s[2:3], 0, v35
	v_lshl_add_u64 v[64:65], v[2:3], 0, v[64:65]
	v_add_u32_e32 v36, -16, v36
	s_or_b64 s[8:9], s[2:3], s[8:9]
	v_mov_b32_e32 v37, v98
	global_store_short_d16_hi v[64:65], v66, off
	s_andn2_b64 exec, exec, s[8:9]
	s_cbranch_execnz .LBB0_672
	s_or_b64 exec, exec, s[8:9]
	v_readlane_b32 s2, v254, 8
	s_nop 1
	v_add_u32_e32 v30, s2, v30
	s_mov_b32 s2, 0x8ffff
	v_cmp_lt_i32_e32 vcc, s2, v30
	s_or_b64 s[6:7], vcc, s[6:7]
	s_andn2_b64 exec, exec, s[6:7]
	s_cbranch_execnz .LBB0_671
